# W1 K-loop: per-block setprio toggles replaced by one static priority raise for the trailing wave half
# speedup vs baseline: 1.0030x; 1.0017x over previous
; #define PG8_STAGE(bufoff, gbase, voff) do { _Pragma("unroll") for (int _i = 0; _i < 2; ++_i) \
;         __builtin_amdgcn_global_load_lds((const unsigned*)((const char*)(gbase) + (voff)[_i]), (LAS unsigned*)(lds + (bufoff) + ldsw + _i * 8192), 16, 0, 0); } while (0)
; #define PG8_LDA(dst, b, h) do { _Pragma("unroll") for (int m = 0; m < 4; ++m) _Pragma("unroll") for (int k = 0; k < 2; ++k) dst[m][k] = *(const LAS bf16x8*)(lds + PG8_SA(b, h) + aoff + m * 2048 + k * 1024); } while (0)
; #define PG8_LDB(dst, b, h) do { _Pragma("unroll") for (int n = 0; n < 2; ++n) _Pragma("unroll") for (int k = 0; k < 2; ++k) dst[n][k] = *(const LAS bf16x8*)(lds + PG8_SB(b, h) + boff + n * 2048 + k * 1024); } while (0)
; #define PG8_MMA(ai, bj, At, Bt) do { __builtin_amdgcn_s_setprio(1); _Pragma("unroll") for (int m = 0; m < 4; ++m) _Pragma("unroll") for (int n = 0; n < 2; ++n) _Pragma("unroll") for (int k = 0; k < 2; ++k) \
;         acc[ai][bj][m][n] = __builtin_amdgcn_mfma_f32_16x16x32_bf16(Bt[n][k], At[m][k], acc[ai][bj][m][n], 0, 0, 0); __builtin_amdgcn_s_setprio(0); } while (0)
; template <class Epi>
; __device__ __forceinline__ void gemm_phase(LAS unsigned char* lds, const Gemm g, const Epi& E) {
;     ...
;         const bool has_next = S.next(ui + 1, nxt);
;         const char* nA = has_next ? (const char*)g.A + (size_t)nxt.bz * g.strideA * 2 + (size_t)nxt.pm * tstepA : cA;
;         const char* nB = has_next ? (const char*)g.Bt + (size_t)nxt.bz * g.strideB * 2 + (size_t)nxt.pn * tstepB : cB;
;         for (int t = 0; t < nt; t += 2) {
;             const bool last = (t == nt - 2);
;             const char* a1 = cA + (size_t)(t + 1) * kstep;
;             const char* a2 = last ? nA : cA + (size_t)(t + 2) * kstep; const char* b2 = last ? nB : cB + (size_t)(t + 2) * kstep;
;             const char* a3 = a2 + kstep; const char* b3 = b2 + kstep;
;             PG8_LDB(B0, 0, 0); PG8_LDB(B1, 0, 1); PG8_SCHED; PG8_LDA(At, 0, 0); PG8_STAGE(PG8_SA(1, 1), a1 + hstepA, voffA);
;             PG8_WAIT_V(8); PG8_WAIT_L(0); PG8_BAR; PG8_MMA(0, 0, At, B0); PG8_MMA(0, 1, At, B1); PG8_BAR; PG8_SCHED;
;     ...
; #pragma unroll
;         for (int a = 0; a < 2; ++a)
; #pragma unroll
;             for (int b = 0; b < 2; ++b)
; #pragma unroll
;                 for (int m = 0; m < 4; ++m)
; #pragma unroll
;                     for (int n = 0; n < 2; ++n) acc[a][b][m][n] = (f32x4){0.f, 0.f, 0.f, 0.f};
.LBB0_607:
	s_ashr_i32 s21, s20, 31
	s_lshl_b64 s[26:27], s[20:21], 19
	s_add_u32 s26, s8, s26
	s_addc_u32 s27, s9, s27
	s_and_b64 s[28:29], s[40:41], exec
	s_cselect_b32 s21, s27, s37
	s_cselect_b32 s31, s26, s36
	s_ashr_i32 s23, s22, 31
	s_lshl_b64 s[28:29], s[22:23], 19
	s_add_u32 s28, s10, s28
	s_addc_u32 s29, s11, s29
	s_and_b64 s[42:43], s[40:41], exec
	s_cselect_b32 s23, s29, s39
	s_cselect_b32 s66, s28, s38
	s_add_u32 s36, s36, 0x40080
	s_addc_u32 s37, s37, 0
	s_add_u32 s68, s38, 0x100
	v_mov_b64_e32 v[0:1], 0
	v_mov_b64_e32 v[2:3], 0
	v_mov_b64_e32 v[4:5], 0
	v_mov_b64_e32 v[6:7], 0
	v_mov_b64_e32 v[8:9], 0
	v_mov_b64_e32 v[10:11], 0
	v_mov_b64_e32 v[12:13], 0
	v_mov_b64_e32 v[14:15], 0
	v_mov_b64_e32 v[16:17], 0
	v_mov_b64_e32 v[18:19], 0
	v_mov_b64_e32 v[20:21], 0
	v_mov_b64_e32 v[22:23], 0
	v_mov_b64_e32 v[24:25], 0
	v_mov_b64_e32 v[26:27], 0
	v_mov_b64_e32 v[28:29], 0
	v_mov_b64_e32 v[30:31], 0
	v_mov_b64_e32 v[32:33], 0
	v_mov_b64_e32 v[34:35], 0
	v_mov_b64_e32 v[36:37], 0
	v_mov_b64_e32 v[38:39], 0
	v_mov_b64_e32 v[40:41], 0
	v_mov_b64_e32 v[42:43], 0
	v_mov_b64_e32 v[44:45], 0
	v_mov_b64_e32 v[46:47], 0
	v_mov_b64_e32 v[48:49], 0
	v_mov_b64_e32 v[50:51], 0
	v_mov_b64_e32 v[52:53], 0
	v_mov_b64_e32 v[54:55], 0
	v_mov_b64_e32 v[56:57], 0
	v_mov_b64_e32 v[58:59], 0
	v_mov_b64_e32 v[60:61], 0
	v_mov_b64_e32 v[62:63], 0
	v_mov_b64_e32 v[64:65], 0
	v_mov_b64_e32 v[66:67], 0
	v_mov_b64_e32 v[68:69], 0
	v_mov_b64_e32 v[70:71], 0
	v_mov_b64_e32 v[72:73], 0
	v_mov_b64_e32 v[74:75], 0
	v_mov_b64_e32 v[76:77], 0
	v_mov_b64_e32 v[78:79], 0
	v_mov_b64_e32 v[80:81], 0
	v_mov_b64_e32 v[82:83], 0
	v_mov_b64_e32 v[84:85], 0
	v_mov_b64_e32 v[86:87], 0
	v_mov_b64_e32 v[88:89], 0
	v_mov_b64_e32 v[90:91], 0
	v_mov_b64_e32 v[92:93], 0
	v_mov_b64_e32 v[94:95], 0
	v_mov_b64_e32 v[96:97], 0
	v_mov_b64_e32 v[98:99], 0
	v_mov_b64_e32 v[100:101], 0
	v_mov_b64_e32 v[102:103], 0
	v_mov_b64_e32 v[104:105], 0
	v_mov_b64_e32 v[106:107], 0
	v_mov_b64_e32 v[108:109], 0
	v_mov_b64_e32 v[110:111], 0
	v_mov_b64_e32 v[112:113], 0
	v_mov_b64_e32 v[114:115], 0
	v_mov_b64_e32 v[116:117], 0
	v_mov_b64_e32 v[118:119], 0
	v_mov_b64_e32 v[120:121], 0
	v_mov_b64_e32 v[122:123], 0
	v_mov_b64_e32 v[124:125], 0
	v_mov_b64_e32 v[126:127], 0
	s_addc_u32 s69, s39, 0
	s_mov_b32 s76, -2
	v_add_u32_e32 v149, 0x10000, v145
	s_and_b64 vcc, exec, s[18:19]
	s_cbranch_scc1 .Lw1_prio_lead
	s_setprio 1
.Lw1_prio_lead:
.LBB0_608:
	s_add_u32 s38, s36, 0xfffc0080
	s_addc_u32 s39, s37, -1
	s_cmp_eq_u32 s76, 12
	s_cselect_b32 s43, s21, s39
	s_cselect_b32 s42, s31, s38
	s_cselect_b32 s39, s23, s69
	s_cselect_b32 s38, s66, s68
	ds_read_b128 v[140:143], v149
	ds_read_b128 v[150:153], v149 offset:1024
	ds_read_b128 v[154:157], v149 offset:2048
	ds_read_b128 v[158:161], v149 offset:3072
	ds_read_b128 v[162:165], v149 offset:16384
	ds_read_b128 v[166:169], v149 offset:17408
	ds_read_b128 v[170:173], v149 offset:18432
	ds_read_b128 v[174:177], v149 offset:19456
	s_add_i32 m0, s13, 0xc000
	ds_read_b128 v[178:181], v148
	ds_read_b128 v[202:205], v148 offset:1024
	ds_read_b128 v[206:209], v148 offset:2048
	ds_read_b128 v[210:213], v148 offset:3072
	ds_read_b128 v[214:217], v148 offset:4096
	ds_read_b128 v[218:221], v148 offset:5120
	ds_read_b128 v[222:225], v148 offset:6144
	ds_read_b128 v[244:247], v148 offset:7168
	global_load_lds_dwordx4 v136, s[36:37]
	s_add_i32 m0, s13, 0xe000
	s_nop 0
	global_load_lds_dwordx4 v138, s[36:37]
	s_waitcnt vmcnt(8)
	s_waitcnt lgkmcnt(0)
	s_barrier
	s_waitcnt lgkmcnt(0)
	v_mfma_f32_16x16x32_bf16 v[124:127], v[140:143], v[178:181], v[124:127]
	v_mfma_f32_16x16x32_bf16 v[116:119], v[154:157], v[178:181], v[116:119]
	v_mfma_f32_16x16x32_bf16 v[108:111], v[140:143], v[206:209], v[108:111]
	v_mfma_f32_16x16x32_bf16 v[100:103], v[154:157], v[206:209], v[100:103]
	v_mfma_f32_16x16x32_bf16 v[92:95], v[140:143], v[214:217], v[92:95]
	v_mfma_f32_16x16x32_bf16 v[84:87], v[154:157], v[214:217], v[84:87]
	v_mfma_f32_16x16x32_bf16 v[76:79], v[140:143], v[222:225], v[76:79]
	v_mfma_f32_16x16x32_bf16 v[68:71], v[154:157], v[222:225], v[68:71]
	v_mfma_f32_16x16x32_bf16 v[124:127], v[150:153], v[202:205], v[124:127]
	v_mfma_f32_16x16x32_bf16 v[116:119], v[158:161], v[202:205], v[116:119]
	v_mfma_f32_16x16x32_bf16 v[108:111], v[150:153], v[210:213], v[108:111]
	v_mfma_f32_16x16x32_bf16 v[100:103], v[158:161], v[210:213], v[100:103]
	v_mfma_f32_16x16x32_bf16 v[92:95], v[150:153], v[218:221], v[92:95]
	v_mfma_f32_16x16x32_bf16 v[84:87], v[158:161], v[218:221], v[84:87]
	v_mfma_f32_16x16x32_bf16 v[76:79], v[150:153], v[244:247], v[76:79]
	v_mfma_f32_16x16x32_bf16 v[68:71], v[158:161], v[244:247], v[68:71]
	v_mfma_f32_16x16x32_bf16 v[120:123], v[162:165], v[178:181], v[120:123]
	v_mfma_f32_16x16x32_bf16 v[112:115], v[170:173], v[178:181], v[112:115]
	v_mfma_f32_16x16x32_bf16 v[104:107], v[162:165], v[206:209], v[104:107]
	v_mfma_f32_16x16x32_bf16 v[96:99], v[170:173], v[206:209], v[96:99]
	v_mfma_f32_16x16x32_bf16 v[88:91], v[162:165], v[214:217], v[88:91]
	v_mfma_f32_16x16x32_bf16 v[80:83], v[170:173], v[214:217], v[80:83]
	v_mfma_f32_16x16x32_bf16 v[72:75], v[162:165], v[222:225], v[72:75]
	v_mfma_f32_16x16x32_bf16 v[64:67], v[170:173], v[222:225], v[64:67]
	v_mfma_f32_16x16x32_bf16 v[120:123], v[166:169], v[202:205], v[120:123]
	v_mfma_f32_16x16x32_bf16 v[112:115], v[174:177], v[202:205], v[112:115]
	v_mfma_f32_16x16x32_bf16 v[104:107], v[166:169], v[210:213], v[104:107]
	v_mfma_f32_16x16x32_bf16 v[96:99], v[174:177], v[210:213], v[96:99]
	v_mfma_f32_16x16x32_bf16 v[88:91], v[166:169], v[218:221], v[88:91]
	v_mfma_f32_16x16x32_bf16 v[80:83], v[174:177], v[218:221], v[80:83]
	v_mfma_f32_16x16x32_bf16 v[72:75], v[166:169], v[244:247], v[72:75]
	v_mfma_f32_16x16x32_bf16 v[64:67], v[174:177], v[244:247], v[64:67]
	s_barrier
; #define PG8_STAGE(bufoff, gbase, voff) do { _Pragma("unroll") for (int _i = 0; _i < 2; ++_i) \
;         __builtin_amdgcn_global_load_lds((const unsigned*)((const char*)(gbase) + (voff)[_i]), (LAS unsigned*)(lds + (bufoff) + ldsw + _i * 8192), 16, 0, 0); } while (0)
; #define PG8_LDA(dst, b, h) do { _Pragma("unroll") for (int m = 0; m < 4; ++m) _Pragma("unroll") for (int k = 0; k < 2; ++k) dst[m][k] = *(const LAS bf16x8*)(lds + PG8_SA(b, h) + aoff + m * 2048 + k * 1024); } while (0)
; #define PG8_LDB(dst, b, h) do { _Pragma("unroll") for (int n = 0; n < 2; ++n) _Pragma("unroll") for (int k = 0; k < 2; ++k) dst[n][k] = *(const LAS bf16x8*)(lds + PG8_SB(b, h) + boff + n * 2048 + k * 1024); } while (0)
; #define PG8_MMA(ai, bj, At, Bt) do { __builtin_amdgcn_s_setprio(1); _Pragma("unroll") for (int m = 0; m < 4; ++m) _Pragma("unroll") for (int n = 0; n < 2; ++n) _Pragma("unroll") for (int k = 0; k < 2; ++k) \
;         acc[ai][bj][m][n] = __builtin_amdgcn_mfma_f32_16x16x32_bf16(Bt[n][k], At[m][k], acc[ai][bj][m][n], 0, 0, 0); __builtin_amdgcn_s_setprio(0); } while (0)
; #define PG8_WAIT_V(n) asm volatile("s_waitcnt vmcnt(" #n ")" ::: "memory")
; #define PG8_WAIT_L(n) asm volatile("s_waitcnt lgkmcnt(" #n ")" ::: "memory")
; #define PG8_BAR __builtin_amdgcn_s_barrier()
; #define PG8_SCHED __builtin_amdgcn_sched_barrier(0)
; template <class Epi>
; __device__ __forceinline__ void gemm_phase(LAS unsigned char* lds, const Gemm g, const Epi& E) {
;     ...
;             PG8_LDA(At, 0, 1); PG8_STAGE(PG8_SB(0, 0), b2, voffB); PG8_STAGE(PG8_SB(0, 1), b2 + hstepB, voffB); PG8_STAGE(PG8_SA(0, 0), a2, voffA);
;             PG8_WAIT_V(8); PG8_WAIT_L(0); PG8_BAR; PG8_MMA(1, 0, At, B0); PG8_MMA(1, 1, At, B1); PG8_BAR; PG8_SCHED;
;             PG8_LDB(B0, 1, 0); PG8_LDB(B1, 1, 1); PG8_SCHED; PG8_LDA(At, 1, 0); PG8_STAGE(PG8_SA(0, 1), a2 + hstepA, voffA);
;             PG8_WAIT_V(8); PG8_WAIT_L(0); PG8_BAR; PG8_MMA(0, 0, At, B0); PG8_MMA(0, 1, At, B1); PG8_BAR; PG8_SCHED;
	s_add_i32 s77, s12, 0x10000
	s_mov_b32 m0, s77
	ds_read_b128 v[178:181], v148 offset:16384
	ds_read_b128 v[202:205], v148 offset:17408
	ds_read_b128 v[206:209], v148 offset:18432
	ds_read_b128 v[210:213], v148 offset:19456
	ds_read_b128 v[214:217], v148 offset:20480
	ds_read_b128 v[218:221], v148 offset:21504
	ds_read_b128 v[222:225], v148 offset:22528
	ds_read_b128 v[244:247], v148 offset:23552
	global_load_lds_dwordx4 v130, s[38:39]
	s_add_i32 m0, s77, 0x2000
	s_add_u32 s82, s38, 0x40000
	s_addc_u32 s83, s39, 0
	s_add_i32 s77, s12, 0x14000
	global_load_lds_dwordx4 v134, s[38:39]
	s_mov_b32 m0, s77
	s_nop 0
	global_load_lds_dwordx4 v130, s[82:83]
	s_add_i32 m0, s77, 0x2000
	s_nop 0
	global_load_lds_dwordx4 v134, s[82:83]
	s_mov_b32 m0, s13
	s_nop 0
	global_load_lds_dwordx4 v128, s[42:43]
	s_mov_b32 m0, s35
	s_nop 0
	global_load_lds_dwordx4 v132, s[42:43]
	s_waitcnt vmcnt(8)
	s_waitcnt lgkmcnt(0)
	s_barrier
	s_waitcnt lgkmcnt(0)
	v_mfma_f32_16x16x32_bf16 v[60:63], v[140:143], v[178:181], v[60:63]
	v_mfma_f32_16x16x32_bf16 v[52:55], v[154:157], v[178:181], v[52:55]
	v_mfma_f32_16x16x32_bf16 v[44:47], v[140:143], v[206:209], v[44:47]
	v_mfma_f32_16x16x32_bf16 v[36:39], v[154:157], v[206:209], v[36:39]
	v_mfma_f32_16x16x32_bf16 v[28:31], v[140:143], v[214:217], v[28:31]
	v_mfma_f32_16x16x32_bf16 v[20:23], v[154:157], v[214:217], v[20:23]
	v_mfma_f32_16x16x32_bf16 v[12:15], v[140:143], v[222:225], v[12:15]
	v_mfma_f32_16x16x32_bf16 v[4:7], v[154:157], v[222:225], v[4:7]
	v_mfma_f32_16x16x32_bf16 v[60:63], v[150:153], v[202:205], v[60:63]
	v_mfma_f32_16x16x32_bf16 v[52:55], v[158:161], v[202:205], v[52:55]
	v_mfma_f32_16x16x32_bf16 v[44:47], v[150:153], v[210:213], v[44:47]
	v_mfma_f32_16x16x32_bf16 v[36:39], v[158:161], v[210:213], v[36:39]
	v_mfma_f32_16x16x32_bf16 v[28:31], v[150:153], v[218:221], v[28:31]
	v_mfma_f32_16x16x32_bf16 v[20:23], v[158:161], v[218:221], v[20:23]
	v_mfma_f32_16x16x32_bf16 v[12:15], v[150:153], v[244:247], v[12:15]
	v_mfma_f32_16x16x32_bf16 v[4:7], v[158:161], v[244:247], v[4:7]
	v_mfma_f32_16x16x32_bf16 v[56:59], v[162:165], v[178:181], v[56:59]
	v_mfma_f32_16x16x32_bf16 v[48:51], v[170:173], v[178:181], v[48:51]
	v_mfma_f32_16x16x32_bf16 v[40:43], v[162:165], v[206:209], v[40:43]
	v_mfma_f32_16x16x32_bf16 v[32:35], v[170:173], v[206:209], v[32:35]
	v_mfma_f32_16x16x32_bf16 v[24:27], v[162:165], v[214:217], v[24:27]
	v_mfma_f32_16x16x32_bf16 v[16:19], v[170:173], v[214:217], v[16:19]
	v_mfma_f32_16x16x32_bf16 v[8:11], v[162:165], v[222:225], v[8:11]
	v_mfma_f32_16x16x32_bf16 v[0:3], v[170:173], v[222:225], v[0:3]
	v_mfma_f32_16x16x32_bf16 v[56:59], v[166:169], v[202:205], v[56:59]
	v_mfma_f32_16x16x32_bf16 v[48:51], v[174:177], v[202:205], v[48:51]
	v_mfma_f32_16x16x32_bf16 v[40:43], v[166:169], v[210:213], v[40:43]
	v_mfma_f32_16x16x32_bf16 v[32:35], v[174:177], v[210:213], v[32:35]
	v_mfma_f32_16x16x32_bf16 v[24:27], v[166:169], v[218:221], v[24:27]
	v_mfma_f32_16x16x32_bf16 v[16:19], v[174:177], v[218:221], v[16:19]
	v_mfma_f32_16x16x32_bf16 v[8:11], v[166:169], v[244:247], v[8:11]
	v_mfma_f32_16x16x32_bf16 v[0:3], v[174:177], v[244:247], v[0:3]
	s_barrier
	ds_read_b128 v[140:143], v149 offset:32768
	ds_read_b128 v[150:153], v149 offset:33792
	ds_read_b128 v[154:157], v149 offset:34816
	ds_read_b128 v[158:161], v149 offset:35840
	ds_read_b128 v[162:165], v149 offset:49152
	ds_read_b128 v[166:169], v149 offset:50176
	ds_read_b128 v[170:173], v149 offset:51200
	ds_read_b128 v[174:177], v149 offset:52224
	s_add_u32 s82, s42, 0x40000
	s_addc_u32 s83, s43, 0
	s_mov_b32 m0, s49
	ds_read_b128 v[178:181], v148 offset:32768
	ds_read_b128 v[202:205], v148 offset:33792
	ds_read_b128 v[206:209], v148 offset:34816
	ds_read_b128 v[210:213], v148 offset:35840
	ds_read_b128 v[214:217], v148 offset:36864
	ds_read_b128 v[218:221], v148 offset:37888
	ds_read_b128 v[222:225], v148 offset:38912
	ds_read_b128 v[244:247], v148 offset:39936
	global_load_lds_dwordx4 v128, s[82:83]
	s_mov_b32 m0, s54
	s_nop 0
	global_load_lds_dwordx4 v132, s[82:83]
	s_waitcnt vmcnt(8)
	s_waitcnt lgkmcnt(0)
	s_barrier
; #define PG8_STAGE(bufoff, gbase, voff) do { _Pragma("unroll") for (int _i = 0; _i < 2; ++_i) \
;         __builtin_amdgcn_global_load_lds((const unsigned*)((const char*)(gbase) + (voff)[_i]), (LAS unsigned*)(lds + (bufoff) + ldsw + _i * 8192), 16, 0, 0); } while (0)
; #define PG8_LDA(dst, b, h) do { _Pragma("unroll") for (int m = 0; m < 4; ++m) _Pragma("unroll") for (int k = 0; k < 2; ++k) dst[m][k] = *(const LAS bf16x8*)(lds + PG8_SA(b, h) + aoff + m * 2048 + k * 1024); } while (0)
; #define PG8_MMA(ai, bj, At, Bt) do { __builtin_amdgcn_s_setprio(1); _Pragma("unroll") for (int m = 0; m < 4; ++m) _Pragma("unroll") for (int n = 0; n < 2; ++n) _Pragma("unroll") for (int k = 0; k < 2; ++k) \
;         acc[ai][bj][m][n] = __builtin_amdgcn_mfma_f32_16x16x32_bf16(Bt[n][k], At[m][k], acc[ai][bj][m][n], 0, 0, 0); __builtin_amdgcn_s_setprio(0); } while (0)
; #define PG8_WAIT_V(n) asm volatile("s_waitcnt vmcnt(" #n ")" ::: "memory")
; #define PG8_WAIT_L(n) asm volatile("s_waitcnt lgkmcnt(" #n ")" ::: "memory")
; #define PG8_BAR __builtin_amdgcn_s_barrier()
; #define PG8_SCHED __builtin_amdgcn_sched_barrier(0)
; template <class Epi>
; __device__ __forceinline__ void gemm_phase(LAS unsigned char* lds, const Gemm g, const Epi& E) {
;     ...
;             PG8_WAIT_V(8); PG8_WAIT_L(0); PG8_BAR; PG8_MMA(0, 0, At, B0); PG8_MMA(0, 1, At, B1); PG8_BAR; PG8_SCHED;
;             PG8_LDA(At, 1, 1); PG8_STAGE(PG8_SB(1, 0), b3, voffB); PG8_STAGE(PG8_SB(1, 1), b3 + hstepB, voffB); PG8_STAGE(PG8_SA(1, 0), a3, voffA);
;             PG8_WAIT_V(8); PG8_WAIT_L(0); PG8_BAR; PG8_MMA(1, 0, At, B0); PG8_MMA(1, 1, At, B1); PG8_BAR; PG8_SCHED;
;         }
;         if (wr == 0) PG8_BAR;
	s_waitcnt lgkmcnt(0)
	v_mfma_f32_16x16x32_bf16 v[124:127], v[140:143], v[178:181], v[124:127]
	v_mfma_f32_16x16x32_bf16 v[116:119], v[154:157], v[178:181], v[116:119]
	v_mfma_f32_16x16x32_bf16 v[108:111], v[140:143], v[206:209], v[108:111]
	v_mfma_f32_16x16x32_bf16 v[100:103], v[154:157], v[206:209], v[100:103]
	v_mfma_f32_16x16x32_bf16 v[92:95], v[140:143], v[214:217], v[92:95]
	v_mfma_f32_16x16x32_bf16 v[84:87], v[154:157], v[214:217], v[84:87]
	v_mfma_f32_16x16x32_bf16 v[76:79], v[140:143], v[222:225], v[76:79]
	v_mfma_f32_16x16x32_bf16 v[68:71], v[154:157], v[222:225], v[68:71]
	v_mfma_f32_16x16x32_bf16 v[124:127], v[150:153], v[202:205], v[124:127]
	v_mfma_f32_16x16x32_bf16 v[116:119], v[158:161], v[202:205], v[116:119]
	v_mfma_f32_16x16x32_bf16 v[108:111], v[150:153], v[210:213], v[108:111]
	v_mfma_f32_16x16x32_bf16 v[100:103], v[158:161], v[210:213], v[100:103]
	v_mfma_f32_16x16x32_bf16 v[92:95], v[150:153], v[218:221], v[92:95]
	v_mfma_f32_16x16x32_bf16 v[84:87], v[158:161], v[218:221], v[84:87]
	v_mfma_f32_16x16x32_bf16 v[76:79], v[150:153], v[244:247], v[76:79]
	v_mfma_f32_16x16x32_bf16 v[68:71], v[158:161], v[244:247], v[68:71]
	v_mfma_f32_16x16x32_bf16 v[120:123], v[162:165], v[178:181], v[120:123]
	v_mfma_f32_16x16x32_bf16 v[112:115], v[170:173], v[178:181], v[112:115]
	v_mfma_f32_16x16x32_bf16 v[104:107], v[162:165], v[206:209], v[104:107]
	v_mfma_f32_16x16x32_bf16 v[96:99], v[170:173], v[206:209], v[96:99]
	v_mfma_f32_16x16x32_bf16 v[88:91], v[162:165], v[214:217], v[88:91]
	v_mfma_f32_16x16x32_bf16 v[80:83], v[170:173], v[214:217], v[80:83]
	v_mfma_f32_16x16x32_bf16 v[72:75], v[162:165], v[222:225], v[72:75]
	v_mfma_f32_16x16x32_bf16 v[64:67], v[170:173], v[222:225], v[64:67]
	v_mfma_f32_16x16x32_bf16 v[120:123], v[166:169], v[202:205], v[120:123]
	v_mfma_f32_16x16x32_bf16 v[112:115], v[174:177], v[202:205], v[112:115]
	v_mfma_f32_16x16x32_bf16 v[104:107], v[166:169], v[210:213], v[104:107]
	v_mfma_f32_16x16x32_bf16 v[96:99], v[174:177], v[210:213], v[96:99]
	v_mfma_f32_16x16x32_bf16 v[88:91], v[166:169], v[218:221], v[88:91]
	v_mfma_f32_16x16x32_bf16 v[80:83], v[174:177], v[218:221], v[80:83]
	v_mfma_f32_16x16x32_bf16 v[72:75], v[166:169], v[244:247], v[72:75]
	v_mfma_f32_16x16x32_bf16 v[64:67], v[174:177], v[244:247], v[64:67]
	s_barrier
	s_add_i32 s77, s12, 0x18000
	s_add_u32 s82, s38, 0x80
	s_addc_u32 s83, s39, 0
	s_mov_b32 m0, s77
	ds_read_b128 v[178:181], v148 offset:49152
	ds_read_b128 v[202:205], v148 offset:50176
	ds_read_b128 v[206:209], v148 offset:51200
	ds_read_b128 v[210:213], v148 offset:52224
	ds_read_b128 v[214:217], v148 offset:53248
	ds_read_b128 v[218:221], v148 offset:54272
	ds_read_b128 v[222:225], v148 offset:55296
	ds_read_b128 v[244:247], v148 offset:56320
	global_load_lds_dwordx4 v130, s[82:83]
	s_add_i32 m0, s77, 0x2000
	s_add_u32 s38, s38, 0x40080
	s_addc_u32 s39, s39, 0
	s_add_i32 s77, s12, 0x1c000
	global_load_lds_dwordx4 v134, s[82:83]
	s_mov_b32 m0, s77
	s_nop 0
	global_load_lds_dwordx4 v130, s[38:39]
	s_add_i32 m0, s77, 0x2000
	s_nop 0
	global_load_lds_dwordx4 v134, s[38:39]
	s_add_u32 s82, s42, 0x80
	s_addc_u32 s83, s43, 0
	s_mov_b32 m0, s55
	s_nop 0
	global_load_lds_dwordx4 v128, s[82:83]
	s_mov_b32 m0, s56
	s_nop 0
	global_load_lds_dwordx4 v132, s[82:83]
	s_waitcnt vmcnt(8)
	s_waitcnt lgkmcnt(0)
	s_barrier
	s_waitcnt lgkmcnt(0)
	v_mfma_f32_16x16x32_bf16 v[60:63], v[140:143], v[178:181], v[60:63]
	v_mfma_f32_16x16x32_bf16 v[52:55], v[154:157], v[178:181], v[52:55]
	v_mfma_f32_16x16x32_bf16 v[44:47], v[140:143], v[206:209], v[44:47]
	v_mfma_f32_16x16x32_bf16 v[36:39], v[154:157], v[206:209], v[36:39]
	v_mfma_f32_16x16x32_bf16 v[28:31], v[140:143], v[214:217], v[28:31]
	v_mfma_f32_16x16x32_bf16 v[20:23], v[154:157], v[214:217], v[20:23]
	v_mfma_f32_16x16x32_bf16 v[12:15], v[140:143], v[222:225], v[12:15]
	v_mfma_f32_16x16x32_bf16 v[4:7], v[154:157], v[222:225], v[4:7]
	v_mfma_f32_16x16x32_bf16 v[60:63], v[150:153], v[202:205], v[60:63]
	v_mfma_f32_16x16x32_bf16 v[52:55], v[158:161], v[202:205], v[52:55]
	v_mfma_f32_16x16x32_bf16 v[44:47], v[150:153], v[210:213], v[44:47]
	v_mfma_f32_16x16x32_bf16 v[36:39], v[158:161], v[210:213], v[36:39]
	v_mfma_f32_16x16x32_bf16 v[28:31], v[150:153], v[218:221], v[28:31]
	v_mfma_f32_16x16x32_bf16 v[20:23], v[158:161], v[218:221], v[20:23]
	v_mfma_f32_16x16x32_bf16 v[12:15], v[150:153], v[244:247], v[12:15]
	v_mfma_f32_16x16x32_bf16 v[4:7], v[158:161], v[244:247], v[4:7]
	v_mfma_f32_16x16x32_bf16 v[56:59], v[162:165], v[178:181], v[56:59]
	v_mfma_f32_16x16x32_bf16 v[48:51], v[170:173], v[178:181], v[48:51]
	v_mfma_f32_16x16x32_bf16 v[40:43], v[162:165], v[206:209], v[40:43]
	v_mfma_f32_16x16x32_bf16 v[32:35], v[170:173], v[206:209], v[32:35]
	v_mfma_f32_16x16x32_bf16 v[24:27], v[162:165], v[214:217], v[24:27]
	v_mfma_f32_16x16x32_bf16 v[16:19], v[170:173], v[214:217], v[16:19]
	v_mfma_f32_16x16x32_bf16 v[8:11], v[162:165], v[222:225], v[8:11]
	v_mfma_f32_16x16x32_bf16 v[0:3], v[170:173], v[222:225], v[0:3]
	v_mfma_f32_16x16x32_bf16 v[56:59], v[166:169], v[202:205], v[56:59]
	v_mfma_f32_16x16x32_bf16 v[48:51], v[174:177], v[202:205], v[48:51]
	v_mfma_f32_16x16x32_bf16 v[40:43], v[166:169], v[210:213], v[40:43]
	v_mfma_f32_16x16x32_bf16 v[32:35], v[174:177], v[210:213], v[32:35]
	v_mfma_f32_16x16x32_bf16 v[24:27], v[166:169], v[218:221], v[24:27]
	v_mfma_f32_16x16x32_bf16 v[16:19], v[174:177], v[218:221], v[16:19]
	v_mfma_f32_16x16x32_bf16 v[8:11], v[166:169], v[244:247], v[8:11]
	v_mfma_f32_16x16x32_bf16 v[0:3], v[174:177], v[244:247], v[0:3]
	s_barrier
	s_add_i32 s76, s76, 2
	s_add_u32 s36, s36, 0x100
	s_addc_u32 s37, s37, 0
	s_add_u32 s68, s68, 0x100
	s_addc_u32 s69, s69, 0
	s_cmp_gt_u32 s76, 13
	s_cbranch_scc0 .LBB0_608
	s_setprio 0
	s_and_b64 vcc, exec, s[18:19]
	s_cbranch_vccz .LBB0_611
	s_barrier
